# MLA attention: one-barrier half offset with a static priority raise for the trail half (diff/SWA lockstep as before)
# baseline (speedup 1.0000x reference)
.LBB0_178:
.LBB0_191:
	ds_read_b128 v[112:115], v209 offset:0
	ds_read_b128 v[116:119], v209 offset:32
	ds_read_b128 v[120:123], v209 offset:64
	ds_read_b128 v[124:127], v209 offset:96
	ds_read_b128 v[250:253], v209 offset:128
	s_cmp_eq_u32 s55, 0
	s_cbranch_scc1 .Latt_mlaL_dmaend
	s_add_i32 s30, s55, 1
	s_cmp_ge_u32 s30, s20
	s_cselect_b64 s[60:61], -1, 0
	s_cbranch_scc1 .Latt_mlaL_dmaend
	s_cmp_lt_u32 s55, 3
	s_cselect_b32 s62, s51, s49
	s_sub_i32 s62, s62, 64
	s_mul_i32 s57, s53, 0x6400
	s_add_i32 s57, s57, s42
	s_mov_b32 m0, s57
	v_mad_u32_u24 v217, s62, v237, v222
	global_load_lds_dwordx4 v217, s[2:3]
	s_add_i32 m0, s57, 0x2000
	v_mad_u32_u24 v217, s62, v239, v224
	global_load_lds_dwordx4 v217, s[2:3]
	s_add_i32 m0, s57, 0x4000
	v_mad_u32_u24 v217, s62, v241, v226
	global_load_lds_dwordx4 v217, s[2:3]
	s_ashr_i32 s63, s62, 31
	s_lshl_b64 s[30:31], s[62:63], 1
	s_mul_i32 s63, s53, 0x4800
	s_add_i32 s63, s63, s42
	s_add_i32 m0, s63, 0x12c00
	s_add_u32 s30, s21, s30
	s_addc_u32 s31, s43, s31
	global_load_lds_dwordx4 v202, s[30:31]
	s_add_i32 m0, s63, 0x14c00
	s_and_b64 vcc, exec, s[18:19]
	global_load_lds_dwordx4 v200, s[30:31]
	s_cbranch_vccz .Latt_mlaL_dmax

.Latt_mlaL_norescale:
	v_exp_f32_e32 v64, v64
	v_exp_f32_e32 v65, v65
	v_exp_f32_e32 v66, v66
	v_exp_f32_e32 v67, v67
	v_exp_f32_e32 v68, v68
	v_exp_f32_e32 v69, v69
	v_exp_f32_e32 v70, v70
	v_exp_f32_e32 v71, v71
	v_cvt_pk_bf16_f32 v124, v64, v65
	v_cvt_pk_bf16_f32 v125, v66, v67
	v_cvt_pk_bf16_f32 v126, v68, v69
	v_cvt_pk_bf16_f32 v127, v70, v71
	s_waitcnt lgkmcnt(1)
	s_nop 0
	v_mfma_f32_32x32x16_bf16 v[48:63], v[112:115], v[124:127], v[48:63]
	ds_read_b128 v[112:115], v219 offset:13824
	v_exp_f32_e32 v72, v72
	v_exp_f32_e32 v73, v73
	v_exp_f32_e32 v74, v74
	v_exp_f32_e32 v75, v75
	v_mfma_f32_32x32x16_bf16 v[32:47], v[116:119], v[124:127], v[32:47]
	ds_read_b128 v[116:119], v219 offset:32
	v_cvt_pk_bf16_f32 v250, v72, v73
	v_exp_f32_e32 v76, v76
	v_exp_f32_e32 v77, v77
	v_cvt_pk_bf16_f32 v251, v74, v75
	s_waitcnt lgkmcnt(1)
	v_mfma_f32_32x32x16_bf16 v[16:31], v[120:123], v[124:127], v[16:31]
	ds_read_b128 v[120:123], v219 offset:4640
	v_exp_f32_e32 v78, v78
	v_exp_f32_e32 v79, v79
	v_cvt_pk_bf16_f32 v252, v76, v77
	v_cvt_pk_bf16_f32 v253, v78, v79
	v_mfma_f32_32x32x16_bf16 v[0:15], v[112:115], v[124:127], v[0:15]
	ds_read_b128 v[112:115], v219 offset:9248
	v_add_f32_e32 v209, v64, v68
	v_add_f32_e32 v211, v65, v69
	v_add_f32_e32 v213, v66, v70
	v_add_f32_e32 v215, v67, v71
	s_waitcnt lgkmcnt(1)
	v_mfma_f32_32x32x16_bf16 v[48:63], v[116:119], v[250:253], v[48:63]
	ds_read_b128 v[64:67], v219 offset:13856
	ds_read_b128 v[68:71], v219 offset:64
	v_exp_f32_e32 v80, v80
	v_exp_f32_e32 v81, v81
	v_exp_f32_e32 v82, v82
	v_exp_f32_e32 v83, v83
	v_cvt_pk_bf16_f32 v124, v80, v81
	v_mfma_f32_32x32x16_bf16 v[32:47], v[120:123], v[250:253], v[32:47]
	ds_read_b128 v[116:119], v219 offset:4672
	ds_read_b128 v[120:123], v219 offset:9280
	v_exp_f32_e32 v84, v84
	v_exp_f32_e32 v85, v85
	v_cvt_pk_bf16_f32 v125, v82, v83
	v_exp_f32_e32 v86, v86
	v_exp_f32_e32 v87, v87
	s_waitcnt lgkmcnt(3)
	v_mfma_f32_32x32x16_bf16 v[16:31], v[112:115], v[250:253], v[16:31]
	ds_read_b128 v[112:115], v219 offset:13888
	v_cvt_pk_bf16_f32 v126, v84, v85
	v_cvt_pk_bf16_f32 v127, v86, v87
	v_add_f32_e32 v209, v209, v72
	v_add_f32_e32 v211, v211, v73
	v_add_f32_e32 v213, v213, v74
	v_mfma_f32_32x32x16_bf16 v[0:15], v[64:67], v[250:253], v[0:15]
	ds_read_b128 v[64:67], v219 offset:96
	v_add_f32_e32 v215, v215, v75
	v_add_f32_e32 v209, v209, v76
	v_add_f32_e32 v211, v211, v77
	v_add_f32_e32 v213, v213, v78
	v_add_f32_e32 v215, v215, v79
	s_waitcnt lgkmcnt(3)
	v_mfma_f32_32x32x16_bf16 v[48:63], v[68:71], v[124:127], v[48:63]
	ds_read_b128 v[72:75], v219 offset:4704
	ds_read_b128 v[76:79], v219 offset:9312
	v_exp_f32_e32 v88, v88
	v_exp_f32_e32 v89, v89
	v_exp_f32_e32 v90, v90
	v_exp_f32_e32 v91, v91
	v_cvt_pk_bf16_f32 v250, v88, v89
	v_mfma_f32_32x32x16_bf16 v[32:47], v[116:119], v[124:127], v[32:47]
	ds_read_b128 v[68:71], v219 offset:13920
	v_exp_f32_e32 v92, v92
	v_exp_f32_e32 v93, v93
	v_cvt_pk_bf16_f32 v251, v90, v91
	v_exp_f32_e32 v94, v94
	v_exp_f32_e32 v95, v95
	s_waitcnt lgkmcnt(4)
	v_mfma_f32_32x32x16_bf16 v[16:31], v[120:123], v[124:127], v[16:31]
	v_cvt_pk_bf16_f32 v252, v92, v93
	v_cvt_pk_bf16_f32 v253, v94, v95
	v_add_f32_e32 v209, v209, v80
	v_add_f32_e32 v211, v211, v81
	v_add_f32_e32 v213, v213, v82
	v_mfma_f32_32x32x16_bf16 v[0:15], v[112:115], v[124:127], v[0:15]
	v_add_f32_e32 v215, v215, v83
	v_add_f32_e32 v209, v209, v84
	v_add_f32_e32 v211, v211, v85
	v_add_f32_e32 v213, v213, v86
	v_add_f32_e32 v215, v215, v87
	s_waitcnt lgkmcnt(2)
	v_mfma_f32_32x32x16_bf16 v[48:63], v[64:67], v[250:253], v[48:63]
	v_add_f32_e32 v209, v209, v88
	v_add_f32_e32 v211, v211, v89
	v_mfma_f32_32x32x16_bf16 v[32:47], v[72:75], v[250:253], v[32:47]
	v_add_f32_e32 v213, v213, v90
	v_add_f32_e32 v215, v215, v91
	s_waitcnt lgkmcnt(0)
	v_mfma_f32_32x32x16_bf16 v[16:31], v[76:79], v[250:253], v[16:31]
	v_add_f32_e32 v209, v209, v92
	v_add_f32_e32 v211, v211, v93
	v_mfma_f32_32x32x16_bf16 v[0:15], v[68:71], v[250:253], v[0:15]
	v_add_f32_e32 v213, v213, v94
	v_add_f32_e32 v215, v215, v95
	v_add_f32_e32 v209, v209, v211
	v_add_f32_e32 v213, v213, v215
	v_add_f32_e32 v209, v209, v213
	v_add_f32_e32 v205, v205, v209
	s_waitcnt vmcnt(0)
	s_add_i32 s30, s52, 1
	s_cmp_lg_u32 s52, 2
	s_cselect_b32 s57, s30, 0
	s_add_i32 s55, s55, 1
	s_add_i32 s49, s49, 64
	s_add_i32 s51, s51, 64
	s_mov_b32 s56, s53
	s_mov_b32 s53, s52
	s_mov_b32 s52, s57
	s_mul_i32 s30, s56, 0x6400
	v_add_u32_e32 v209, s30, v246
	s_mul_i32 s30, s56, 0x4800
	v_add_u32_e32 v219, s30, v247
	s_cmp_eq_u32 s20, s55
	s_waitcnt lgkmcnt(0)
	s_barrier
	s_cbranch_scc0 .LBB0_178
	s_barrier
	s_setprio 0
	s_branch .LBB0_153
.Latt_mlaT_pre:
	s_setprio 1
.Latt_mlaT_top:
	ds_read_b128 v[112:115], v209 offset:0
	ds_read_b128 v[116:119], v209 offset:32
	ds_read_b128 v[120:123], v209 offset:64
	ds_read_b128 v[124:127], v209 offset:96
	ds_read_b128 v[250:253], v209 offset:128
	s_waitcnt lgkmcnt(3)
	v_mfma_f32_32x32x16_bf16 v[64:79], v[112:115], v[130:133], v[96:111]
	ds_read_b128 v[112:115], v209 offset:160
	v_mfma_f32_32x32x16_bf16 v[64:79], v[116:119], v[134:137], v[64:79]
	ds_read_b128 v[116:119], v209 offset:192
	s_waitcnt lgkmcnt(3)
	v_mfma_f32_32x32x16_bf16 v[64:79], v[120:123], v[138:141], v[64:79]
	ds_read_b128 v[120:123], v209 offset:224
	v_mfma_f32_32x32x16_bf16 v[64:79], v[124:127], v[142:145], v[64:79]
	ds_read_b128 v[124:127], v209 offset:256
	s_waitcnt lgkmcnt(3)
	v_mfma_f32_32x32x16_bf16 v[64:79], v[250:253], v[146:149], v[64:79]
	ds_read_b128 v[250:253], v209 offset:288
	v_mfma_f32_32x32x16_bf16 v[64:79], v[112:115], v[150:153], v[64:79]
	ds_read_b128 v[112:115], v209 offset:320
	s_waitcnt lgkmcnt(3)
	v_mfma_f32_32x32x16_bf16 v[64:79], v[116:119], v[154:157], v[64:79]
	ds_read_b128 v[116:119], v209 offset:352
	v_mfma_f32_32x32x16_bf16 v[64:79], v[120:123], v[158:161], v[64:79]
	ds_read_b128 v[120:123], v209 offset:12800
	s_waitcnt lgkmcnt(3)
	v_mfma_f32_32x32x16_bf16 v[64:79], v[124:127], v[162:165], v[64:79]
	ds_read_b128 v[124:127], v209 offset:12832
	v_mfma_f32_32x32x16_bf16 v[64:79], v[250:253], v[166:169], v[64:79]
	ds_read_b128 v[250:253], v209 offset:12864
	s_waitcnt lgkmcnt(3)
	v_mfma_f32_32x32x16_bf16 v[64:79], v[112:115], v[170:173], v[64:79]
	ds_read_b128 v[112:115], v209 offset:12896
	v_mfma_f32_32x32x16_bf16 v[64:79], v[116:119], v[174:177], v[64:79]
	ds_read_b128 v[116:119], v209 offset:12928
	s_waitcnt lgkmcnt(3)
	v_mfma_f32_32x32x16_bf16 v[80:95], v[120:123], v[130:133], v[96:111]
	ds_read_b128 v[120:123], v209 offset:12960
	v_mfma_f32_32x32x16_bf16 v[80:95], v[124:127], v[134:137], v[80:95]
	ds_read_b128 v[124:127], v209 offset:12992
	s_waitcnt lgkmcnt(3)
	v_mfma_f32_32x32x16_bf16 v[80:95], v[250:253], v[138:141], v[80:95]
	ds_read_b128 v[250:253], v209 offset:13024
	v_mfma_f32_32x32x16_bf16 v[80:95], v[112:115], v[142:145], v[80:95]
	ds_read_b128 v[112:115], v209 offset:13056
	s_waitcnt lgkmcnt(3)
	v_mfma_f32_32x32x16_bf16 v[80:95], v[116:119], v[146:149], v[80:95]
	ds_read_b128 v[116:119], v209 offset:13088
	v_max3_f32 v211, v64, v65, v66
	v_mfma_f32_32x32x16_bf16 v[80:95], v[120:123], v[150:153], v[80:95]
	ds_read_b128 v[120:123], v209 offset:13120
	v_max3_f32 v213, v67, v68, v69
	s_waitcnt lgkmcnt(3)
	v_mfma_f32_32x32x16_bf16 v[80:95], v[124:127], v[154:157], v[80:95]
	ds_read_b128 v[124:127], v209 offset:13152
	v_max3_f32 v211, v211, v70, v71
	v_mfma_f32_32x32x16_bf16 v[80:95], v[250:253], v[158:161], v[80:95]
	v_max3_f32 v213, v213, v72, v73
	s_waitcnt lgkmcnt(2)
	v_mfma_f32_32x32x16_bf16 v[80:95], v[112:115], v[162:165], v[80:95]
	v_max3_f32 v211, v211, v74, v75
	v_mfma_f32_32x32x16_bf16 v[80:95], v[116:119], v[166:169], v[80:95]
	v_max3_f32 v213, v213, v76, v77
	s_waitcnt lgkmcnt(0)
	v_mfma_f32_32x32x16_bf16 v[80:95], v[120:123], v[170:173], v[80:95]
	v_max3_f32 v211, v211, v78, v79
	v_mfma_f32_32x32x16_bf16 v[80:95], v[124:127], v[174:177], v[80:95]
	ds_read_b128 v[112:115], v219 offset:0
	ds_read_b128 v[116:119], v219 offset:4608
	ds_read_b128 v[120:123], v219 offset:9216
	s_cmp_eq_u32 s55, 0
	s_cselect_b32 s31, 0xff7fffff, 0
	s_nop 6
	v_max3_f32 v215, v80, v81, v82
	v_max3_f32 v209, v83, v84, v85
	v_max3_f32 v215, v215, v86, v87
	v_max3_f32 v209, v209, v88, v89
	v_max3_f32 v215, v215, v90, v91
	v_max3_f32 v209, v209, v92, v93
	v_max3_f32 v215, v215, v94, v95
	v_max3_f32 v209, v209, v211, v213
	v_max_f32_e32 v209, v209, v215
	v_cmp_lt_f32_e32 vcc, s58, v209
	s_cmp_eq_u32 s55, 0
	s_cbranch_scc1 .Latt_mlaT_rare
	s_cbranch_vccnz .Latt_mlaT_rare

.Latt_mlaT_dmaend:
	s_waitcnt lgkmcnt(1)
	s_nop 0
	v_mfma_f32_32x32x16_bf16 v[48:63], v[112:115], v[124:127], v[48:63]
	ds_read_b128 v[112:115], v219 offset:13824
	v_exp_f32_e32 v72, v72
	v_exp_f32_e32 v73, v73
	v_exp_f32_e32 v74, v74
	v_exp_f32_e32 v75, v75
	v_mfma_f32_32x32x16_bf16 v[32:47], v[116:119], v[124:127], v[32:47]
	ds_read_b128 v[116:119], v219 offset:32
	v_cvt_pk_bf16_f32 v250, v72, v73
	v_exp_f32_e32 v76, v76
	v_exp_f32_e32 v77, v77
	v_cvt_pk_bf16_f32 v251, v74, v75
	s_waitcnt lgkmcnt(1)
	v_mfma_f32_32x32x16_bf16 v[16:31], v[120:123], v[124:127], v[16:31]
	ds_read_b128 v[120:123], v219 offset:4640
	v_exp_f32_e32 v78, v78
	v_exp_f32_e32 v79, v79
	v_cvt_pk_bf16_f32 v252, v76, v77
	v_cvt_pk_bf16_f32 v253, v78, v79
	v_mfma_f32_32x32x16_bf16 v[0:15], v[112:115], v[124:127], v[0:15]
	ds_read_b128 v[112:115], v219 offset:9248
	v_add_f32_e32 v209, v64, v68
	v_add_f32_e32 v211, v65, v69
	v_add_f32_e32 v213, v66, v70
	v_add_f32_e32 v215, v67, v71
	s_waitcnt lgkmcnt(1)
	v_mfma_f32_32x32x16_bf16 v[48:63], v[116:119], v[250:253], v[48:63]
	ds_read_b128 v[64:67], v219 offset:13856
	ds_read_b128 v[68:71], v219 offset:64
	v_exp_f32_e32 v80, v80
	v_exp_f32_e32 v81, v81
	v_exp_f32_e32 v82, v82
	v_exp_f32_e32 v83, v83
	v_cvt_pk_bf16_f32 v124, v80, v81
	v_mfma_f32_32x32x16_bf16 v[32:47], v[120:123], v[250:253], v[32:47]
	ds_read_b128 v[116:119], v219 offset:4672
	ds_read_b128 v[120:123], v219 offset:9280
	v_exp_f32_e32 v84, v84
	v_exp_f32_e32 v85, v85
	v_cvt_pk_bf16_f32 v125, v82, v83
	v_exp_f32_e32 v86, v86
	v_exp_f32_e32 v87, v87
	s_waitcnt lgkmcnt(3)
	v_mfma_f32_32x32x16_bf16 v[16:31], v[112:115], v[250:253], v[16:31]
	ds_read_b128 v[112:115], v219 offset:13888
	v_cvt_pk_bf16_f32 v126, v84, v85
	v_cvt_pk_bf16_f32 v127, v86, v87
	v_add_f32_e32 v209, v209, v72
	v_add_f32_e32 v211, v211, v73
	v_add_f32_e32 v213, v213, v74
	v_mfma_f32_32x32x16_bf16 v[0:15], v[64:67], v[250:253], v[0:15]
	ds_read_b128 v[64:67], v219 offset:96
	v_add_f32_e32 v215, v215, v75
	v_add_f32_e32 v209, v209, v76
	v_add_f32_e32 v211, v211, v77
	v_add_f32_e32 v213, v213, v78
	v_add_f32_e32 v215, v215, v79
	s_waitcnt lgkmcnt(3)
	v_mfma_f32_32x32x16_bf16 v[48:63], v[68:71], v[124:127], v[48:63]
	ds_read_b128 v[72:75], v219 offset:4704
	ds_read_b128 v[76:79], v219 offset:9312
	v_exp_f32_e32 v88, v88
	v_exp_f32_e32 v89, v89
	v_exp_f32_e32 v90, v90
	v_exp_f32_e32 v91, v91
	v_cvt_pk_bf16_f32 v250, v88, v89
	v_mfma_f32_32x32x16_bf16 v[32:47], v[116:119], v[124:127], v[32:47]
	ds_read_b128 v[68:71], v219 offset:13920
	v_exp_f32_e32 v92, v92
	v_exp_f32_e32 v93, v93
	v_cvt_pk_bf16_f32 v251, v90, v91
	v_exp_f32_e32 v94, v94
	v_exp_f32_e32 v95, v95
	s_waitcnt lgkmcnt(4)
	v_mfma_f32_32x32x16_bf16 v[16:31], v[120:123], v[124:127], v[16:31]
	v_cvt_pk_bf16_f32 v252, v92, v93
	v_cvt_pk_bf16_f32 v253, v94, v95
	v_add_f32_e32 v209, v209, v80
	v_add_f32_e32 v211, v211, v81
	v_add_f32_e32 v213, v213, v82
	v_mfma_f32_32x32x16_bf16 v[0:15], v[112:115], v[124:127], v[0:15]
	v_add_f32_e32 v215, v215, v83
	v_add_f32_e32 v209, v209, v84
	v_add_f32_e32 v211, v211, v85
	v_add_f32_e32 v213, v213, v86
	v_add_f32_e32 v215, v215, v87
	s_waitcnt lgkmcnt(2)
	v_mfma_f32_32x32x16_bf16 v[48:63], v[64:67], v[250:253], v[48:63]
	v_add_f32_e32 v209, v209, v88
	v_add_f32_e32 v211, v211, v89
	v_mfma_f32_32x32x16_bf16 v[32:47], v[72:75], v[250:253], v[32:47]
	v_add_f32_e32 v213, v213, v90
	v_add_f32_e32 v215, v215, v91
	s_waitcnt lgkmcnt(0)
	v_mfma_f32_32x32x16_bf16 v[16:31], v[76:79], v[250:253], v[16:31]
	v_add_f32_e32 v209, v209, v92
	v_add_f32_e32 v211, v211, v93
	v_mfma_f32_32x32x16_bf16 v[0:15], v[68:71], v[250:253], v[0:15]
	v_add_f32_e32 v213, v213, v94
	v_add_f32_e32 v215, v215, v95
	v_add_f32_e32 v209, v209, v211
	v_add_f32_e32 v213, v213, v215
	v_add_f32_e32 v209, v209, v213
	v_add_f32_e32 v205, v205, v209
	s_add_i32 s30, s52, 1
	s_cmp_lg_u32 s52, 2
	s_cselect_b32 s57, s30, 0
	s_add_i32 s55, s55, 1
	s_add_i32 s49, s49, 64
	s_add_i32 s51, s51, 64
	s_mov_b32 s56, s53
	s_mov_b32 s53, s52
	s_mov_b32 s52, s57
	s_mul_i32 s30, s56, 0x6400
	v_add_u32_e32 v209, s30, v246
	s_mul_i32 s30, s56, 0x4800
	v_add_u32_e32 v219, s30, v247
	s_cmp_eq_u32 s20, s55
	s_cbranch_scc0 .Latt_mlaT_top
	s_barrier
	s_setprio 0
	s_branch .LBB0_153
